# P0: half the workgroups (cid bit3) run the weight conversions before the activation stream instead of after
# baseline (speedup 1.0000x reference)
.LBB0_20:
	s_or_b64 exec, exec, s[0:1]
	v_readlane_b32 s0, v246, 4
	v_readlane_b32 s1, v246, 5
	s_cmp_lt_i32 s0, 1
	s_cselect_b64 s[2:3], -1, 0
	s_cmp_gt_i32 s1, 0
	s_cselect_b64 s[0:1], -1, 0
	s_and_b64 s[0:1], s[2:3], s[0:1]
	s_andn2_b64 vcc, exec, s[0:1]
	s_cbranch_vccnz .LBB0_190
	s_mov_b32 s97, 0
	s_bitcmp1_b32 s30, 3
	s_cbranch_scc0 .Lp0_act
	s_mov_b32 s97, 1
	s_branch .Lp0_conv
.Lp0_act:
	v_lshrrev_b32_e32 v0, 3, v202
	v_and_b32_e32 v0, 0x78, v0
	v_lshl_add_u32 v0, s30, 6, v0
	s_mov_b32 s0, 0x8c00
	v_cmp_gt_i32_e32 vcc, s0, v0
	s_and_saveexec_b64 s[4:5], vcc
	s_cbranch_execz .LBB0_104
	s_add_u32 s6, s22, 0x5e00000
	s_addc_u32 s7, s23, 0
	s_add_u32 s8, s22, 0x6221000
	s_addc_u32 s9, s23, 0
	v_mbcnt_lo_u32_b32 v2, -1, 0
	s_add_u32 s10, s22, 0x1c00000
	v_mbcnt_hi_u32_b32 v2, -1, v2
	v_and_b32_e32 v1, 63, v202
	s_addc_u32 s11, s23, 0
	v_and_b32_e32 v3, 64, v2
	v_readlane_b32 s0, v246, 1
	s_add_u32 s12, s22, 0x6200000
	v_lshlrev_b32_e32 v128, 2, v1
	v_add_u32_e32 v3, 64, v3
	v_cmp_eq_u32_e32 vcc, 0, v1
	v_readlane_b32 s1, v246, 2
	v_xor_b32_e32 v1, 1, v2
	s_addc_u32 s13, s23, 0
	s_lshl_b32 s18, s0, 6
	v_cmp_lt_i32_e64 s[0:1], v1, v3
	v_mov_b32_e32 v131, 0
	v_add_u32_e32 v132, 0xffff7c00, v0
	v_cndmask_b32_e64 v1, v2, v1, s[0:1]
	v_lshlrev_b32_e32 v129, 2, v1
	v_xor_b32_e32 v1, 2, v2
	v_cmp_lt_i32_e64 s[0:1], v1, v3
	s_mov_b64 s[14:15], 0
	s_movk_i32 s19, 0x7fff
	v_cndmask_b32_e64 v1, v2, v1, s[0:1]
	v_lshlrev_b32_e32 v166, 2, v1
	v_xor_b32_e32 v1, 4, v2
	v_cmp_lt_i32_e64 s[0:1], v1, v3
	s_mov_b32 s24, 0x83ff
	v_mov_b32_e32 v171, 0x358637bd
	v_cndmask_b32_e64 v1, v2, v1, s[0:1]
	v_lshlrev_b32_e32 v167, 2, v1
	v_xor_b32_e32 v1, 8, v2
	v_cmp_lt_i32_e64 s[0:1], v1, v3
	s_mov_b32 s25, 0x8bff
	s_nop 0
	v_cndmask_b32_e64 v1, v2, v1, s[0:1]
	v_lshlrev_b32_e32 v168, 2, v1
	v_xor_b32_e32 v1, 16, v2
	v_cmp_lt_i32_e64 s[0:1], v1, v3
	s_nop 1
	v_cndmask_b32_e64 v1, v2, v1, s[0:1]
	v_lshlrev_b32_e32 v169, 2, v1
	v_xor_b32_e32 v1, 32, v2
	v_cmp_lt_i32_e64 s[0:1], v1, v3
	s_nop 1
	v_cndmask_b32_e64 v1, v2, v1, s[0:1]
	v_lshlrev_b32_e32 v170, 2, v1
	s_branch .LBB0_24

.LBB0_104:
	s_or_b64 exec, exec, s[4:5]
	s_cmp_eq_u32 s97, 2
	s_cbranch_scc1 .LBB0_190
.Lp0_conv:
	v_readlane_b32 s0, v246, 1
	s_lshl_b32 s16, s0, 9
	v_lshl_add_u32 v36, s30, 9, v202
	s_mov_b32 s0, 0x16000
	v_cmp_gt_i32_e64 s[4:5], s0, v36
	v_readlane_b32 s1, v246, 2
	s_and_saveexec_b64 s[6:7], s[4:5]
	s_cbranch_execz .LBB0_123
	v_readlane_b32 s36, v246, 22
	v_readlane_b32 s37, v246, 23
	s_cmp_lg_u64 s[36:37], 0
	s_cselect_b64 s[0:1], -1, 0
	v_lshlrev_b32_e32 v0, 3, v202
	v_readlane_b32 s10, v246, 1
	v_lshl_add_u32 v37, s30, 12, v0
	v_readlane_b32 s11, v246, 2
	v_cndmask_b32_e64 v0, 0, 1, s[0:1]
	s_mov_b64 s[8:9], 0
	s_lshl_b32 s10, s10, 12
	s_mov_b32 s11, 0x2e8ba2e9
	s_movk_i32 s12, 0x58
	s_movk_i32 s13, 0x2c00
	v_cmp_ne_u32_e64 s[0:1], 1, v0
	s_mov_b32 s14, 0x15fff
	v_mov_b32_e32 v38, v36
	v_readlane_b32 s38, v246, 24
	v_readlane_b32 s39, v246, 25
	v_readlane_b32 s40, v246, 26
	v_readlane_b32 s41, v246, 27
	v_readlane_b32 s42, v246, 28
	v_readlane_b32 s43, v246, 29
	v_readlane_b32 s44, v246, 30
	v_readlane_b32 s45, v246, 31
	v_readlane_b32 s46, v246, 32
	v_readlane_b32 s47, v246, 33
	v_readlane_b32 s48, v246, 34
	v_readlane_b32 s49, v246, 35
	v_readlane_b32 s50, v246, 36
	v_readlane_b32 s51, v246, 37
	s_branch .LBB0_107

.LBB0_189:
	s_or_b64 exec, exec, s[0:1]
	s_cmp_eq_u32 s97, 1
	s_cbranch_scc0 .Lp0_fin
	s_mov_b32 s97, 2
	s_branch .Lp0_act
.Lp0_fin:
.LBB0_190:
	v_readlane_b32 s0, v246, 4
	v_readlane_b32 s1, v246, 5
	s_cmp_gt_i32 s1, 1
	s_cselect_b64 s[4:5], -1, 0
	s_and_b64 s[0:1], s[2:3], s[4:5]
	s_andn2_b64 vcc, exec, s[0:1]
	s_mov_b32 s0, s30
	v_writelane_b32 v246, s0, 60
	s_nop 1
	v_writelane_b32 v246, s1, 61
	s_cbranch_vccnz .LBB0_244
	s_waitcnt vmcnt(0)
	s_waitcnt lgkmcnt(0)
	s_barrier
	s_mov_b64 s[0:1], exec
	v_readlane_b32 s2, v246, 55
	v_readlane_b32 s3, v246, 56
	s_and_b64 s[2:3], s[0:1], s[2:3]
	s_mov_b64 exec, s[2:3]
	s_cbranch_execz .LBB0_243
	v_readlane_b32 s2, v246, 54
	s_waitcnt vmcnt(0) expcnt(0) lgkmcnt(0)
	s_nop 0
	v_mov_b32_e32 v0, s2
	v_readlane_b32 s2, v246, 0
	ds_read_b32 v2, v0
	s_add_i32 s33, s2, 0x23ff4
	v_mov_b32_e32 v0, s33
	ds_read_b32 v0, v0
	s_waitcnt lgkmcnt(1)
	v_cmp_ne_u32_e32 vcc, 0, v2
	s_cbranch_vccnz .LBB0_207
	v_readlane_b32 s2, v246, 1
	v_readlane_b32 s6, v246, 3
	v_readlane_b32 s3, v246, 2
	s_mul_i32 s50, s6, s2
	s_add_u32 s2, s22, 0x194cd200
	s_mul_i32 s50, s50, s3
	s_addc_u32 s3, s23, 0
	s_add_u32 s6, s22, 0x194cd400
	s_addc_u32 s7, s23, 0
	s_add_u32 s8, s22, 0x194cd500
	s_addc_u32 s9, s23, 0
	s_add_u32 s10, s22, 0x194cd600
	s_addc_u32 s11, s23, 0
	s_add_u32 s12, s22, 0x194cd700
	s_addc_u32 s13, s23, 0
	s_add_u32 s14, s22, 0x194cd800
	s_addc_u32 s15, s23, 0
	s_add_u32 s16, s22, 0x194cd900
	s_addc_u32 s17, s23, 0
	s_add_u32 s18, s22, 0x194cda00
	s_addc_u32 s19, s23, 0
	s_add_u32 s24, s22, 0x194cdb00
	s_addc_u32 s25, s23, 0
	s_add_u32 s26, s22, 0x194cdc00
	s_addc_u32 s27, s23, 0
	s_add_u32 s28, s22, 0x194cdd00
	s_addc_u32 s29, s23, 0
	s_add_u32 s30, s22, 0x194cde00
	s_addc_u32 s31, s23, 0
	s_add_u32 s34, s22, 0x194cdf00
	s_addc_u32 s35, s23, 0
	s_add_u32 s36, s22, 0x194ce000
	s_addc_u32 s37, s23, 0
	s_add_u32 s38, s22, 0x194ce100
	s_addc_u32 s39, s23, 0
	s_add_u32 s40, s22, 0x194ce200
	s_addc_u32 s41, s23, 0
	s_add_u32 s42, s22, 0x194ce300
	s_addc_u32 s43, s23, 0
	s_mov_b32 s51, 1
	v_mov_b32_e32 v16, 0
	s_branch .LBB0_195
